# hand-written compact M_GATE epilogue (straight-line, all loads up front, same math) replacing compiler's branchy per-fragment path
# baseline (speedup 1.0000x reference)
.LBB0_226:
	s_cmp_lg_u32 s62, 4
	s_cbranch_scc1 .Lmy_ng
	v_readlane_b32 s11, v243, 43
	v_readlane_b32 s6, v243, 58
	v_readlane_b32 s7, v243, 59
	v_readlane_b32 s8, v243, 44
	s_lshl_b32 s10, s14, 8
	s_add_i32 s10, s10, s11
	v_add_u32_e32 v144, s10, v190
	v_ashrrev_i32_e32 v145, 31, v144
	s_nop 1
	v_lshl_add_u64 v[146:147], v[144:145], 3, s[6:7]
	global_load_dwordx2 v[214:215], v[146:147], off
	global_load_dwordx2 v[216:217], v[146:147], off offset:128
	global_load_dwordx2 v[218:219], v[146:147], off offset:256
	global_load_dwordx2 v[220:221], v[146:147], off offset:384
	global_load_dwordx2 v[222:223], v[146:147], off offset:1024
	global_load_dwordx2 v[224:225], v[146:147], off offset:1152
	global_load_dwordx2 v[226:227], v[146:147], off offset:1280
	global_load_dwordx2 v[228:229], v[146:147], off offset:1408
	s_lshl_b32 s10, s13, 8
	v_lshl_add_u32 v166, v1, 3, s8
	v_add_u32_e32 v166, s10, v166
	v_ashrrev_i32_e32 v167, 31, v166
	v_lshl_add_u64 v[168:169], v[166:167], 2, s[98:99]
	global_load_dwordx4 v[148:151], v[168:169], off
	global_load_dwordx4 v[152:155], v[168:169], off offset:16
	global_load_dwordx4 v[156:159], v[168:169], off offset:512
	global_load_dwordx4 v[160:163], v[168:169], off offset:528
	v_lshlrev_b64 v[170:171], 10, v[144:145]
	v_lshl_add_u64 v[164:165], s[2:3], 0, v[170:171]
	v_lshl_add_u64 v[164:165], v[164:165], 0, v[166:167]
	s_mov_b32 s50, 0xbfb8aa3b
	s_mov_b32 s82, 0x437f0000
	s_mov_b32 s64, 1.0
	s_mov_b64 s[8:9], 0x4000
	s_mov_b64 s[16:17], 0x14000
	s_nop 7
	s_nop 7
	s_waitcnt vmcnt(0)
	v_ffbh_u32_e32 v174, v215
	v_min_u32_e32 v174, 32, v174
	v_lshlrev_b64 v[214:215], v174, v[214:215]
	v_min_u32_e32 v214, 1, v214
	v_or_b32_e32 v214, v215, v214
	v_cvt_f32_u32_e32 v214, v214
	v_sub_u32_e32 v215, 32, v174
	v_ldexp_f32 v214, v214, v215
	v_fmaak_f32 v214, v192, v214, 0x358637bd
	v_rsq_f32_e32 v172, v214
	s_nop 0
	v_pk_mul_f32 v[126:127], v[126:127], v[172:173] op_sel_hi:[1,0]
	v_pk_mul_f32 v[128:129], v[128:129], v[172:173] op_sel_hi:[1,0]
	v_pk_mul_f32 v[122:123], v[122:123], v[172:173] op_sel_hi:[1,0]
	v_pk_mul_f32 v[124:125], v[124:125], v[172:173] op_sel_hi:[1,0]
	v_pk_add_f32 v[126:127], v[126:127], v[148:149]
	v_pk_add_f32 v[128:129], v[128:129], v[150:151]
	v_pk_add_f32 v[122:123], v[122:123], v[152:153]
	v_pk_add_f32 v[124:125], v[124:125], v[154:155]
	v_pk_mul_f32 v[122:123], v[122:123], s[50:51] op_sel_hi:[1,0]
	v_pk_mul_f32 v[124:125], v[124:125], s[50:51] op_sel_hi:[1,0]
	v_pk_mul_f32 v[126:127], v[126:127], s[50:51] op_sel_hi:[1,0]
	v_pk_mul_f32 v[128:129], v[128:129], s[50:51] op_sel_hi:[1,0]
	v_exp_f32_e32 v122, v122
	v_exp_f32_e32 v123, v123
	v_exp_f32_e32 v124, v124
	v_exp_f32_e32 v125, v125
	v_exp_f32_e32 v126, v126
	v_exp_f32_e32 v127, v127
	v_exp_f32_e32 v128, v128
	v_exp_f32_e32 v129, v129
	v_pk_add_f32 v[122:123], v[122:123], s[64:65] op_sel_hi:[1,0]
	v_pk_add_f32 v[124:125], v[124:125], s[64:65] op_sel_hi:[1,0]
	v_pk_add_f32 v[126:127], v[126:127], s[64:65] op_sel_hi:[1,0]
	v_pk_add_f32 v[128:129], v[128:129], s[64:65] op_sel_hi:[1,0]
	v_rcp_f32_e32 v122, v122
	v_rcp_f32_e32 v123, v123
	v_rcp_f32_e32 v124, v124
	v_rcp_f32_e32 v125, v125
	v_rcp_f32_e32 v126, v126
	v_rcp_f32_e32 v127, v127
	v_rcp_f32_e32 v128, v128
	v_rcp_f32_e32 v129, v129
	v_pk_mul_f32 v[122:123], v[122:123], s[82:83] op_sel_hi:[1,0]
	v_pk_mul_f32 v[124:125], v[124:125], s[82:83] op_sel_hi:[1,0]
	v_pk_mul_f32 v[126:127], v[126:127], s[82:83] op_sel_hi:[1,0]
	v_pk_mul_f32 v[128:129], v[128:129], s[82:83] op_sel_hi:[1,0]
	v_rndne_f32_e32 v122, v122
	v_rndne_f32_e32 v123, v123
	v_rndne_f32_e32 v124, v124
	v_rndne_f32_e32 v125, v125
	v_rndne_f32_e32 v126, v126
	v_rndne_f32_e32 v127, v127
	v_rndne_f32_e32 v128, v128
	v_rndne_f32_e32 v129, v129
	v_cvt_u32_f32_e32 v126, v126
	v_cvt_u32_f32_e32 v127, v127
	v_cvt_u32_f32_e32 v122, v122
	v_cvt_u32_f32_e32 v123, v123
	v_cvt_u32_f32_sdwa v128, v128 dst_sel:WORD_1 dst_unused:UNUSED_PAD src0_sel:DWORD
	v_cvt_u32_f32_sdwa v124, v124 dst_sel:WORD_1 dst_unused:UNUSED_PAD src0_sel:DWORD
	v_cvt_u32_f32_sdwa v129, v129 dst_sel:BYTE_3 dst_unused:UNUSED_PAD src0_sel:DWORD
	v_cvt_u32_f32_sdwa v125, v125 dst_sel:BYTE_3 dst_unused:UNUSED_PAD src0_sel:DWORD
	v_lshl_or_b32 v126, v127, 8, v126
	v_lshl_or_b32 v127, v123, 8, v122
	v_or3_b32 v126, v126, v128, v129
	v_or3_b32 v127, v127, v124, v125
	global_store_dwordx2 v[164:165], v[126:127], off
	v_pk_mul_f32 v[118:119], v[118:119], v[172:173] op_sel_hi:[1,0]
	v_pk_mul_f32 v[120:121], v[120:121], v[172:173] op_sel_hi:[1,0]
	v_pk_mul_f32 v[114:115], v[114:115], v[172:173] op_sel_hi:[1,0]
	v_pk_mul_f32 v[116:117], v[116:117], v[172:173] op_sel_hi:[1,0]
	v_pk_add_f32 v[118:119], v[118:119], v[156:157]
	v_pk_add_f32 v[120:121], v[120:121], v[158:159]
	v_pk_add_f32 v[114:115], v[114:115], v[160:161]
	v_pk_add_f32 v[116:117], v[116:117], v[162:163]
	v_pk_mul_f32 v[114:115], v[114:115], s[50:51] op_sel_hi:[1,0]
	v_pk_mul_f32 v[116:117], v[116:117], s[50:51] op_sel_hi:[1,0]
	v_pk_mul_f32 v[118:119], v[118:119], s[50:51] op_sel_hi:[1,0]
	v_pk_mul_f32 v[120:121], v[120:121], s[50:51] op_sel_hi:[1,0]
	v_exp_f32_e32 v114, v114
	v_exp_f32_e32 v115, v115
	v_exp_f32_e32 v116, v116
	v_exp_f32_e32 v117, v117
	v_exp_f32_e32 v118, v118
	v_exp_f32_e32 v119, v119
	v_exp_f32_e32 v120, v120
	v_exp_f32_e32 v121, v121
	v_pk_add_f32 v[114:115], v[114:115], s[64:65] op_sel_hi:[1,0]
	v_pk_add_f32 v[116:117], v[116:117], s[64:65] op_sel_hi:[1,0]
	v_pk_add_f32 v[118:119], v[118:119], s[64:65] op_sel_hi:[1,0]
	v_pk_add_f32 v[120:121], v[120:121], s[64:65] op_sel_hi:[1,0]
	v_rcp_f32_e32 v114, v114
	v_rcp_f32_e32 v115, v115
	v_rcp_f32_e32 v116, v116
	v_rcp_f32_e32 v117, v117
	v_rcp_f32_e32 v118, v118
	v_rcp_f32_e32 v119, v119
	v_rcp_f32_e32 v120, v120
	v_rcp_f32_e32 v121, v121
	v_pk_mul_f32 v[114:115], v[114:115], s[82:83] op_sel_hi:[1,0]
	v_pk_mul_f32 v[116:117], v[116:117], s[82:83] op_sel_hi:[1,0]
	v_pk_mul_f32 v[118:119], v[118:119], s[82:83] op_sel_hi:[1,0]
	v_pk_mul_f32 v[120:121], v[120:121], s[82:83] op_sel_hi:[1,0]
	v_rndne_f32_e32 v114, v114
	v_rndne_f32_e32 v115, v115
	v_rndne_f32_e32 v116, v116
	v_rndne_f32_e32 v117, v117
	v_rndne_f32_e32 v118, v118
	v_rndne_f32_e32 v119, v119
	v_rndne_f32_e32 v120, v120
	v_rndne_f32_e32 v121, v121
	v_cvt_u32_f32_e32 v118, v118
	v_cvt_u32_f32_e32 v119, v119
	v_cvt_u32_f32_e32 v114, v114
	v_cvt_u32_f32_e32 v115, v115
	v_cvt_u32_f32_sdwa v120, v120 dst_sel:WORD_1 dst_unused:UNUSED_PAD src0_sel:DWORD
	v_cvt_u32_f32_sdwa v116, v116 dst_sel:WORD_1 dst_unused:UNUSED_PAD src0_sel:DWORD
	v_cvt_u32_f32_sdwa v121, v121 dst_sel:BYTE_3 dst_unused:UNUSED_PAD src0_sel:DWORD
	v_cvt_u32_f32_sdwa v117, v117 dst_sel:BYTE_3 dst_unused:UNUSED_PAD src0_sel:DWORD
	v_lshl_or_b32 v118, v119, 8, v118
	v_lshl_or_b32 v119, v115, 8, v114
	v_or3_b32 v118, v118, v120, v121
	v_or3_b32 v119, v119, v116, v117
	global_store_dwordx2 v[164:165], v[118:119], off offset:128
	v_lshl_add_u64 v[164:165], v[164:165], 0, s[8:9]
	v_ffbh_u32_e32 v174, v217
	v_min_u32_e32 v174, 32, v174
	v_lshlrev_b64 v[216:217], v174, v[216:217]
	v_min_u32_e32 v216, 1, v216
	v_or_b32_e32 v216, v217, v216
	v_cvt_f32_u32_e32 v216, v216
	v_sub_u32_e32 v217, 32, v174
	v_ldexp_f32 v216, v216, v217
	v_fmaak_f32 v216, v192, v216, 0x358637bd
	v_rsq_f32_e32 v172, v216
	s_nop 0
	v_pk_mul_f32 v[110:111], v[110:111], v[172:173] op_sel_hi:[1,0]
	v_pk_mul_f32 v[112:113], v[112:113], v[172:173] op_sel_hi:[1,0]
	v_pk_mul_f32 v[106:107], v[106:107], v[172:173] op_sel_hi:[1,0]
	v_pk_mul_f32 v[108:109], v[108:109], v[172:173] op_sel_hi:[1,0]
	v_pk_add_f32 v[110:111], v[110:111], v[148:149]
	v_pk_add_f32 v[112:113], v[112:113], v[150:151]
	v_pk_add_f32 v[106:107], v[106:107], v[152:153]
	v_pk_add_f32 v[108:109], v[108:109], v[154:155]
	v_pk_mul_f32 v[106:107], v[106:107], s[50:51] op_sel_hi:[1,0]
	v_pk_mul_f32 v[108:109], v[108:109], s[50:51] op_sel_hi:[1,0]
	v_pk_mul_f32 v[110:111], v[110:111], s[50:51] op_sel_hi:[1,0]
	v_pk_mul_f32 v[112:113], v[112:113], s[50:51] op_sel_hi:[1,0]
	v_exp_f32_e32 v106, v106
	v_exp_f32_e32 v107, v107
	v_exp_f32_e32 v108, v108
	v_exp_f32_e32 v109, v109
	v_exp_f32_e32 v110, v110
	v_exp_f32_e32 v111, v111
	v_exp_f32_e32 v112, v112
	v_exp_f32_e32 v113, v113
	v_pk_add_f32 v[106:107], v[106:107], s[64:65] op_sel_hi:[1,0]
	v_pk_add_f32 v[108:109], v[108:109], s[64:65] op_sel_hi:[1,0]
	v_pk_add_f32 v[110:111], v[110:111], s[64:65] op_sel_hi:[1,0]
	v_pk_add_f32 v[112:113], v[112:113], s[64:65] op_sel_hi:[1,0]
	v_rcp_f32_e32 v106, v106
	v_rcp_f32_e32 v107, v107
	v_rcp_f32_e32 v108, v108
	v_rcp_f32_e32 v109, v109
	v_rcp_f32_e32 v110, v110
	v_rcp_f32_e32 v111, v111
	v_rcp_f32_e32 v112, v112
	v_rcp_f32_e32 v113, v113
	v_pk_mul_f32 v[106:107], v[106:107], s[82:83] op_sel_hi:[1,0]
	v_pk_mul_f32 v[108:109], v[108:109], s[82:83] op_sel_hi:[1,0]
	v_pk_mul_f32 v[110:111], v[110:111], s[82:83] op_sel_hi:[1,0]
	v_pk_mul_f32 v[112:113], v[112:113], s[82:83] op_sel_hi:[1,0]
	v_rndne_f32_e32 v106, v106
	v_rndne_f32_e32 v107, v107
	v_rndne_f32_e32 v108, v108
	v_rndne_f32_e32 v109, v109
	v_rndne_f32_e32 v110, v110
	v_rndne_f32_e32 v111, v111
	v_rndne_f32_e32 v112, v112
	v_rndne_f32_e32 v113, v113
	v_cvt_u32_f32_e32 v110, v110
	v_cvt_u32_f32_e32 v111, v111
	v_cvt_u32_f32_e32 v106, v106
	v_cvt_u32_f32_e32 v107, v107
	v_cvt_u32_f32_sdwa v112, v112 dst_sel:WORD_1 dst_unused:UNUSED_PAD src0_sel:DWORD
	v_cvt_u32_f32_sdwa v108, v108 dst_sel:WORD_1 dst_unused:UNUSED_PAD src0_sel:DWORD
	v_cvt_u32_f32_sdwa v113, v113 dst_sel:BYTE_3 dst_unused:UNUSED_PAD src0_sel:DWORD
	v_cvt_u32_f32_sdwa v109, v109 dst_sel:BYTE_3 dst_unused:UNUSED_PAD src0_sel:DWORD
	v_lshl_or_b32 v110, v111, 8, v110
	v_lshl_or_b32 v111, v107, 8, v106
	v_or3_b32 v110, v110, v112, v113
	v_or3_b32 v111, v111, v108, v109
	global_store_dwordx2 v[164:165], v[110:111], off
	v_pk_mul_f32 v[102:103], v[102:103], v[172:173] op_sel_hi:[1,0]
	v_pk_mul_f32 v[104:105], v[104:105], v[172:173] op_sel_hi:[1,0]
	v_pk_mul_f32 v[98:99], v[98:99], v[172:173] op_sel_hi:[1,0]
	v_pk_mul_f32 v[100:101], v[100:101], v[172:173] op_sel_hi:[1,0]
	v_pk_add_f32 v[102:103], v[102:103], v[156:157]
	v_pk_add_f32 v[104:105], v[104:105], v[158:159]
	v_pk_add_f32 v[98:99], v[98:99], v[160:161]
	v_pk_add_f32 v[100:101], v[100:101], v[162:163]
	v_pk_mul_f32 v[98:99], v[98:99], s[50:51] op_sel_hi:[1,0]
	v_pk_mul_f32 v[100:101], v[100:101], s[50:51] op_sel_hi:[1,0]
	v_pk_mul_f32 v[102:103], v[102:103], s[50:51] op_sel_hi:[1,0]
	v_pk_mul_f32 v[104:105], v[104:105], s[50:51] op_sel_hi:[1,0]
	v_exp_f32_e32 v98, v98
	v_exp_f32_e32 v99, v99
	v_exp_f32_e32 v100, v100
	v_exp_f32_e32 v101, v101
	v_exp_f32_e32 v102, v102
	v_exp_f32_e32 v103, v103
	v_exp_f32_e32 v104, v104
	v_exp_f32_e32 v105, v105
	v_pk_add_f32 v[98:99], v[98:99], s[64:65] op_sel_hi:[1,0]
	v_pk_add_f32 v[100:101], v[100:101], s[64:65] op_sel_hi:[1,0]
	v_pk_add_f32 v[102:103], v[102:103], s[64:65] op_sel_hi:[1,0]
	v_pk_add_f32 v[104:105], v[104:105], s[64:65] op_sel_hi:[1,0]
	v_rcp_f32_e32 v98, v98
	v_rcp_f32_e32 v99, v99
	v_rcp_f32_e32 v100, v100
	v_rcp_f32_e32 v101, v101
	v_rcp_f32_e32 v102, v102
	v_rcp_f32_e32 v103, v103
	v_rcp_f32_e32 v104, v104
	v_rcp_f32_e32 v105, v105
	v_pk_mul_f32 v[98:99], v[98:99], s[82:83] op_sel_hi:[1,0]
	v_pk_mul_f32 v[100:101], v[100:101], s[82:83] op_sel_hi:[1,0]
	v_pk_mul_f32 v[102:103], v[102:103], s[82:83] op_sel_hi:[1,0]
	v_pk_mul_f32 v[104:105], v[104:105], s[82:83] op_sel_hi:[1,0]
	v_rndne_f32_e32 v98, v98
	v_rndne_f32_e32 v99, v99
	v_rndne_f32_e32 v100, v100
	v_rndne_f32_e32 v101, v101
	v_rndne_f32_e32 v102, v102
	v_rndne_f32_e32 v103, v103
	v_rndne_f32_e32 v104, v104
	v_rndne_f32_e32 v105, v105
	v_cvt_u32_f32_e32 v102, v102
	v_cvt_u32_f32_e32 v103, v103
	v_cvt_u32_f32_e32 v98, v98
	v_cvt_u32_f32_e32 v99, v99
	v_cvt_u32_f32_sdwa v104, v104 dst_sel:WORD_1 dst_unused:UNUSED_PAD src0_sel:DWORD
	v_cvt_u32_f32_sdwa v100, v100 dst_sel:WORD_1 dst_unused:UNUSED_PAD src0_sel:DWORD
	v_cvt_u32_f32_sdwa v105, v105 dst_sel:BYTE_3 dst_unused:UNUSED_PAD src0_sel:DWORD
	v_cvt_u32_f32_sdwa v101, v101 dst_sel:BYTE_3 dst_unused:UNUSED_PAD src0_sel:DWORD
	v_lshl_or_b32 v102, v103, 8, v102
	v_lshl_or_b32 v103, v99, 8, v98
	v_or3_b32 v102, v102, v104, v105
	v_or3_b32 v103, v103, v100, v101
	global_store_dwordx2 v[164:165], v[102:103], off offset:128
	v_lshl_add_u64 v[164:165], v[164:165], 0, s[8:9]
	v_ffbh_u32_e32 v174, v219
	v_min_u32_e32 v174, 32, v174
	v_lshlrev_b64 v[218:219], v174, v[218:219]
	v_min_u32_e32 v218, 1, v218
	v_or_b32_e32 v218, v219, v218
	v_cvt_f32_u32_e32 v218, v218
	v_sub_u32_e32 v219, 32, v174
	v_ldexp_f32 v218, v218, v219
	v_fmaak_f32 v218, v192, v218, 0x358637bd
	v_rsq_f32_e32 v172, v218
	s_nop 0
	v_pk_mul_f32 v[94:95], v[94:95], v[172:173] op_sel_hi:[1,0]
	v_pk_mul_f32 v[96:97], v[96:97], v[172:173] op_sel_hi:[1,0]
	v_pk_mul_f32 v[90:91], v[90:91], v[172:173] op_sel_hi:[1,0]
	v_pk_mul_f32 v[92:93], v[92:93], v[172:173] op_sel_hi:[1,0]
	v_pk_add_f32 v[94:95], v[94:95], v[148:149]
	v_pk_add_f32 v[96:97], v[96:97], v[150:151]
	v_pk_add_f32 v[90:91], v[90:91], v[152:153]
	v_pk_add_f32 v[92:93], v[92:93], v[154:155]
	v_pk_mul_f32 v[90:91], v[90:91], s[50:51] op_sel_hi:[1,0]
	v_pk_mul_f32 v[92:93], v[92:93], s[50:51] op_sel_hi:[1,0]
	v_pk_mul_f32 v[94:95], v[94:95], s[50:51] op_sel_hi:[1,0]
	v_pk_mul_f32 v[96:97], v[96:97], s[50:51] op_sel_hi:[1,0]
	v_exp_f32_e32 v90, v90
	v_exp_f32_e32 v91, v91
	v_exp_f32_e32 v92, v92
	v_exp_f32_e32 v93, v93
	v_exp_f32_e32 v94, v94
	v_exp_f32_e32 v95, v95
	v_exp_f32_e32 v96, v96
	v_exp_f32_e32 v97, v97
	v_pk_add_f32 v[90:91], v[90:91], s[64:65] op_sel_hi:[1,0]
	v_pk_add_f32 v[92:93], v[92:93], s[64:65] op_sel_hi:[1,0]
	v_pk_add_f32 v[94:95], v[94:95], s[64:65] op_sel_hi:[1,0]
	v_pk_add_f32 v[96:97], v[96:97], s[64:65] op_sel_hi:[1,0]
	v_rcp_f32_e32 v90, v90
	v_rcp_f32_e32 v91, v91
	v_rcp_f32_e32 v92, v92
	v_rcp_f32_e32 v93, v93
	v_rcp_f32_e32 v94, v94
	v_rcp_f32_e32 v95, v95
	v_rcp_f32_e32 v96, v96
	v_rcp_f32_e32 v97, v97
	v_pk_mul_f32 v[90:91], v[90:91], s[82:83] op_sel_hi:[1,0]
	v_pk_mul_f32 v[92:93], v[92:93], s[82:83] op_sel_hi:[1,0]
	v_pk_mul_f32 v[94:95], v[94:95], s[82:83] op_sel_hi:[1,0]
	v_pk_mul_f32 v[96:97], v[96:97], s[82:83] op_sel_hi:[1,0]
	v_rndne_f32_e32 v90, v90
	v_rndne_f32_e32 v91, v91
	v_rndne_f32_e32 v92, v92
	v_rndne_f32_e32 v93, v93
	v_rndne_f32_e32 v94, v94
	v_rndne_f32_e32 v95, v95
	v_rndne_f32_e32 v96, v96
	v_rndne_f32_e32 v97, v97
	v_cvt_u32_f32_e32 v94, v94
	v_cvt_u32_f32_e32 v95, v95
	v_cvt_u32_f32_e32 v90, v90
	v_cvt_u32_f32_e32 v91, v91
	v_cvt_u32_f32_sdwa v96, v96 dst_sel:WORD_1 dst_unused:UNUSED_PAD src0_sel:DWORD
	v_cvt_u32_f32_sdwa v92, v92 dst_sel:WORD_1 dst_unused:UNUSED_PAD src0_sel:DWORD
	v_cvt_u32_f32_sdwa v97, v97 dst_sel:BYTE_3 dst_unused:UNUSED_PAD src0_sel:DWORD
	v_cvt_u32_f32_sdwa v93, v93 dst_sel:BYTE_3 dst_unused:UNUSED_PAD src0_sel:DWORD
	v_lshl_or_b32 v94, v95, 8, v94
	v_lshl_or_b32 v95, v91, 8, v90
	v_or3_b32 v94, v94, v96, v97
	v_or3_b32 v95, v95, v92, v93
	global_store_dwordx2 v[164:165], v[94:95], off
	v_pk_mul_f32 v[86:87], v[86:87], v[172:173] op_sel_hi:[1,0]
	v_pk_mul_f32 v[88:89], v[88:89], v[172:173] op_sel_hi:[1,0]
	v_pk_mul_f32 v[82:83], v[82:83], v[172:173] op_sel_hi:[1,0]
	v_pk_mul_f32 v[84:85], v[84:85], v[172:173] op_sel_hi:[1,0]
	v_pk_add_f32 v[86:87], v[86:87], v[156:157]
	v_pk_add_f32 v[88:89], v[88:89], v[158:159]
	v_pk_add_f32 v[82:83], v[82:83], v[160:161]
	v_pk_add_f32 v[84:85], v[84:85], v[162:163]
	v_pk_mul_f32 v[82:83], v[82:83], s[50:51] op_sel_hi:[1,0]
	v_pk_mul_f32 v[84:85], v[84:85], s[50:51] op_sel_hi:[1,0]
	v_pk_mul_f32 v[86:87], v[86:87], s[50:51] op_sel_hi:[1,0]
	v_pk_mul_f32 v[88:89], v[88:89], s[50:51] op_sel_hi:[1,0]
	v_exp_f32_e32 v82, v82
	v_exp_f32_e32 v83, v83
	v_exp_f32_e32 v84, v84
	v_exp_f32_e32 v85, v85
	v_exp_f32_e32 v86, v86
	v_exp_f32_e32 v87, v87
	v_exp_f32_e32 v88, v88
	v_exp_f32_e32 v89, v89
	v_pk_add_f32 v[82:83], v[82:83], s[64:65] op_sel_hi:[1,0]
	v_pk_add_f32 v[84:85], v[84:85], s[64:65] op_sel_hi:[1,0]
	v_pk_add_f32 v[86:87], v[86:87], s[64:65] op_sel_hi:[1,0]
	v_pk_add_f32 v[88:89], v[88:89], s[64:65] op_sel_hi:[1,0]
	v_rcp_f32_e32 v82, v82
	v_rcp_f32_e32 v83, v83
	v_rcp_f32_e32 v84, v84
	v_rcp_f32_e32 v85, v85
	v_rcp_f32_e32 v86, v86
	v_rcp_f32_e32 v87, v87
	v_rcp_f32_e32 v88, v88
	v_rcp_f32_e32 v89, v89
	v_pk_mul_f32 v[82:83], v[82:83], s[82:83] op_sel_hi:[1,0]
	v_pk_mul_f32 v[84:85], v[84:85], s[82:83] op_sel_hi:[1,0]
	v_pk_mul_f32 v[86:87], v[86:87], s[82:83] op_sel_hi:[1,0]
	v_pk_mul_f32 v[88:89], v[88:89], s[82:83] op_sel_hi:[1,0]
	v_rndne_f32_e32 v82, v82
	v_rndne_f32_e32 v83, v83
	v_rndne_f32_e32 v84, v84
	v_rndne_f32_e32 v85, v85
	v_rndne_f32_e32 v86, v86
	v_rndne_f32_e32 v87, v87
	v_rndne_f32_e32 v88, v88
	v_rndne_f32_e32 v89, v89
	v_cvt_u32_f32_e32 v86, v86
	v_cvt_u32_f32_e32 v87, v87
	v_cvt_u32_f32_e32 v82, v82
	v_cvt_u32_f32_e32 v83, v83
	v_cvt_u32_f32_sdwa v88, v88 dst_sel:WORD_1 dst_unused:UNUSED_PAD src0_sel:DWORD
	v_cvt_u32_f32_sdwa v84, v84 dst_sel:WORD_1 dst_unused:UNUSED_PAD src0_sel:DWORD
	v_cvt_u32_f32_sdwa v89, v89 dst_sel:BYTE_3 dst_unused:UNUSED_PAD src0_sel:DWORD
	v_cvt_u32_f32_sdwa v85, v85 dst_sel:BYTE_3 dst_unused:UNUSED_PAD src0_sel:DWORD
	v_lshl_or_b32 v86, v87, 8, v86
	v_lshl_or_b32 v87, v83, 8, v82
	v_or3_b32 v86, v86, v88, v89
	v_or3_b32 v87, v87, v84, v85
	global_store_dwordx2 v[164:165], v[86:87], off offset:128
	v_lshl_add_u64 v[164:165], v[164:165], 0, s[8:9]
	v_ffbh_u32_e32 v174, v221
	v_min_u32_e32 v174, 32, v174
	v_lshlrev_b64 v[220:221], v174, v[220:221]
	v_min_u32_e32 v220, 1, v220
	v_or_b32_e32 v220, v221, v220
	v_cvt_f32_u32_e32 v220, v220
	v_sub_u32_e32 v221, 32, v174
	v_ldexp_f32 v220, v220, v221
	v_fmaak_f32 v220, v192, v220, 0x358637bd
	v_rsq_f32_e32 v172, v220
	s_nop 0
	v_pk_mul_f32 v[78:79], v[78:79], v[172:173] op_sel_hi:[1,0]
	v_pk_mul_f32 v[80:81], v[80:81], v[172:173] op_sel_hi:[1,0]
	v_pk_mul_f32 v[74:75], v[74:75], v[172:173] op_sel_hi:[1,0]
	v_pk_mul_f32 v[76:77], v[76:77], v[172:173] op_sel_hi:[1,0]
	v_pk_add_f32 v[78:79], v[78:79], v[148:149]
	v_pk_add_f32 v[80:81], v[80:81], v[150:151]
	v_pk_add_f32 v[74:75], v[74:75], v[152:153]
	v_pk_add_f32 v[76:77], v[76:77], v[154:155]
	v_pk_mul_f32 v[74:75], v[74:75], s[50:51] op_sel_hi:[1,0]
	v_pk_mul_f32 v[76:77], v[76:77], s[50:51] op_sel_hi:[1,0]
	v_pk_mul_f32 v[78:79], v[78:79], s[50:51] op_sel_hi:[1,0]
	v_pk_mul_f32 v[80:81], v[80:81], s[50:51] op_sel_hi:[1,0]
	v_exp_f32_e32 v74, v74
	v_exp_f32_e32 v75, v75
	v_exp_f32_e32 v76, v76
	v_exp_f32_e32 v77, v77
	v_exp_f32_e32 v78, v78
	v_exp_f32_e32 v79, v79
	v_exp_f32_e32 v80, v80
	v_exp_f32_e32 v81, v81
	v_pk_add_f32 v[74:75], v[74:75], s[64:65] op_sel_hi:[1,0]
	v_pk_add_f32 v[76:77], v[76:77], s[64:65] op_sel_hi:[1,0]
	v_pk_add_f32 v[78:79], v[78:79], s[64:65] op_sel_hi:[1,0]
	v_pk_add_f32 v[80:81], v[80:81], s[64:65] op_sel_hi:[1,0]
	v_rcp_f32_e32 v74, v74
	v_rcp_f32_e32 v75, v75
	v_rcp_f32_e32 v76, v76
	v_rcp_f32_e32 v77, v77
	v_rcp_f32_e32 v78, v78
	v_rcp_f32_e32 v79, v79
	v_rcp_f32_e32 v80, v80
	v_rcp_f32_e32 v81, v81
	v_pk_mul_f32 v[74:75], v[74:75], s[82:83] op_sel_hi:[1,0]
	v_pk_mul_f32 v[76:77], v[76:77], s[82:83] op_sel_hi:[1,0]
	v_pk_mul_f32 v[78:79], v[78:79], s[82:83] op_sel_hi:[1,0]
	v_pk_mul_f32 v[80:81], v[80:81], s[82:83] op_sel_hi:[1,0]
	v_rndne_f32_e32 v74, v74
	v_rndne_f32_e32 v75, v75
	v_rndne_f32_e32 v76, v76
	v_rndne_f32_e32 v77, v77
	v_rndne_f32_e32 v78, v78
	v_rndne_f32_e32 v79, v79
	v_rndne_f32_e32 v80, v80
	v_rndne_f32_e32 v81, v81
	v_cvt_u32_f32_e32 v78, v78
	v_cvt_u32_f32_e32 v79, v79
	v_cvt_u32_f32_e32 v74, v74
	v_cvt_u32_f32_e32 v75, v75
	v_cvt_u32_f32_sdwa v80, v80 dst_sel:WORD_1 dst_unused:UNUSED_PAD src0_sel:DWORD
	v_cvt_u32_f32_sdwa v76, v76 dst_sel:WORD_1 dst_unused:UNUSED_PAD src0_sel:DWORD
	v_cvt_u32_f32_sdwa v81, v81 dst_sel:BYTE_3 dst_unused:UNUSED_PAD src0_sel:DWORD
	v_cvt_u32_f32_sdwa v77, v77 dst_sel:BYTE_3 dst_unused:UNUSED_PAD src0_sel:DWORD
	v_lshl_or_b32 v78, v79, 8, v78
	v_lshl_or_b32 v79, v75, 8, v74
	v_or3_b32 v78, v78, v80, v81
	v_or3_b32 v79, v79, v76, v77
	global_store_dwordx2 v[164:165], v[78:79], off
	v_pk_mul_f32 v[70:71], v[70:71], v[172:173] op_sel_hi:[1,0]
	v_pk_mul_f32 v[72:73], v[72:73], v[172:173] op_sel_hi:[1,0]
	v_pk_mul_f32 v[66:67], v[66:67], v[172:173] op_sel_hi:[1,0]
	v_pk_mul_f32 v[68:69], v[68:69], v[172:173] op_sel_hi:[1,0]
	v_pk_add_f32 v[70:71], v[70:71], v[156:157]
	v_pk_add_f32 v[72:73], v[72:73], v[158:159]
	v_pk_add_f32 v[66:67], v[66:67], v[160:161]
	v_pk_add_f32 v[68:69], v[68:69], v[162:163]
	v_pk_mul_f32 v[66:67], v[66:67], s[50:51] op_sel_hi:[1,0]
	v_pk_mul_f32 v[68:69], v[68:69], s[50:51] op_sel_hi:[1,0]
	v_pk_mul_f32 v[70:71], v[70:71], s[50:51] op_sel_hi:[1,0]
	v_pk_mul_f32 v[72:73], v[72:73], s[50:51] op_sel_hi:[1,0]
	v_exp_f32_e32 v66, v66
	v_exp_f32_e32 v67, v67
	v_exp_f32_e32 v68, v68
	v_exp_f32_e32 v69, v69
	v_exp_f32_e32 v70, v70
	v_exp_f32_e32 v71, v71
	v_exp_f32_e32 v72, v72
	v_exp_f32_e32 v73, v73
	v_pk_add_f32 v[66:67], v[66:67], s[64:65] op_sel_hi:[1,0]
	v_pk_add_f32 v[68:69], v[68:69], s[64:65] op_sel_hi:[1,0]
	v_pk_add_f32 v[70:71], v[70:71], s[64:65] op_sel_hi:[1,0]
	v_pk_add_f32 v[72:73], v[72:73], s[64:65] op_sel_hi:[1,0]
	v_rcp_f32_e32 v66, v66
	v_rcp_f32_e32 v67, v67
	v_rcp_f32_e32 v68, v68
	v_rcp_f32_e32 v69, v69
	v_rcp_f32_e32 v70, v70
	v_rcp_f32_e32 v71, v71
	v_rcp_f32_e32 v72, v72
	v_rcp_f32_e32 v73, v73
	v_pk_mul_f32 v[66:67], v[66:67], s[82:83] op_sel_hi:[1,0]
	v_pk_mul_f32 v[68:69], v[68:69], s[82:83] op_sel_hi:[1,0]
	v_pk_mul_f32 v[70:71], v[70:71], s[82:83] op_sel_hi:[1,0]
	v_pk_mul_f32 v[72:73], v[72:73], s[82:83] op_sel_hi:[1,0]
	v_rndne_f32_e32 v66, v66
	v_rndne_f32_e32 v67, v67
	v_rndne_f32_e32 v68, v68
	v_rndne_f32_e32 v69, v69
	v_rndne_f32_e32 v70, v70
	v_rndne_f32_e32 v71, v71
	v_rndne_f32_e32 v72, v72
	v_rndne_f32_e32 v73, v73
	v_cvt_u32_f32_e32 v70, v70
	v_cvt_u32_f32_e32 v71, v71
	v_cvt_u32_f32_e32 v66, v66
	v_cvt_u32_f32_e32 v67, v67
	v_cvt_u32_f32_sdwa v72, v72 dst_sel:WORD_1 dst_unused:UNUSED_PAD src0_sel:DWORD
	v_cvt_u32_f32_sdwa v68, v68 dst_sel:WORD_1 dst_unused:UNUSED_PAD src0_sel:DWORD
	v_cvt_u32_f32_sdwa v73, v73 dst_sel:BYTE_3 dst_unused:UNUSED_PAD src0_sel:DWORD
	v_cvt_u32_f32_sdwa v69, v69 dst_sel:BYTE_3 dst_unused:UNUSED_PAD src0_sel:DWORD
	v_lshl_or_b32 v70, v71, 8, v70
	v_lshl_or_b32 v71, v67, 8, v66
	v_or3_b32 v70, v70, v72, v73
	v_or3_b32 v71, v71, v68, v69
	global_store_dwordx2 v[164:165], v[70:71], off offset:128
	v_lshl_add_u64 v[164:165], v[164:165], 0, s[16:17]
	v_ffbh_u32_e32 v174, v223
	v_min_u32_e32 v174, 32, v174
	v_lshlrev_b64 v[222:223], v174, v[222:223]
	v_min_u32_e32 v222, 1, v222
	v_or_b32_e32 v222, v223, v222
	v_cvt_f32_u32_e32 v222, v222
	v_sub_u32_e32 v223, 32, v174
	v_ldexp_f32 v222, v222, v223
	v_fmaak_f32 v222, v192, v222, 0x358637bd
	v_rsq_f32_e32 v172, v222
	s_nop 0
	v_pk_mul_f32 v[62:63], v[62:63], v[172:173] op_sel_hi:[1,0]
	v_pk_mul_f32 v[64:65], v[64:65], v[172:173] op_sel_hi:[1,0]
	v_pk_mul_f32 v[58:59], v[58:59], v[172:173] op_sel_hi:[1,0]
	v_pk_mul_f32 v[60:61], v[60:61], v[172:173] op_sel_hi:[1,0]
	v_pk_add_f32 v[62:63], v[62:63], v[148:149]
	v_pk_add_f32 v[64:65], v[64:65], v[150:151]
	v_pk_add_f32 v[58:59], v[58:59], v[152:153]
	v_pk_add_f32 v[60:61], v[60:61], v[154:155]
	v_pk_mul_f32 v[58:59], v[58:59], s[50:51] op_sel_hi:[1,0]
	v_pk_mul_f32 v[60:61], v[60:61], s[50:51] op_sel_hi:[1,0]
	v_pk_mul_f32 v[62:63], v[62:63], s[50:51] op_sel_hi:[1,0]
	v_pk_mul_f32 v[64:65], v[64:65], s[50:51] op_sel_hi:[1,0]
	v_exp_f32_e32 v58, v58
	v_exp_f32_e32 v59, v59
	v_exp_f32_e32 v60, v60
	v_exp_f32_e32 v61, v61
	v_exp_f32_e32 v62, v62
	v_exp_f32_e32 v63, v63
	v_exp_f32_e32 v64, v64
	v_exp_f32_e32 v65, v65
	v_pk_add_f32 v[58:59], v[58:59], s[64:65] op_sel_hi:[1,0]
	v_pk_add_f32 v[60:61], v[60:61], s[64:65] op_sel_hi:[1,0]
	v_pk_add_f32 v[62:63], v[62:63], s[64:65] op_sel_hi:[1,0]
	v_pk_add_f32 v[64:65], v[64:65], s[64:65] op_sel_hi:[1,0]
	v_rcp_f32_e32 v58, v58
	v_rcp_f32_e32 v59, v59
	v_rcp_f32_e32 v60, v60
	v_rcp_f32_e32 v61, v61
	v_rcp_f32_e32 v62, v62
	v_rcp_f32_e32 v63, v63
	v_rcp_f32_e32 v64, v64
	v_rcp_f32_e32 v65, v65
	v_pk_mul_f32 v[58:59], v[58:59], s[82:83] op_sel_hi:[1,0]
	v_pk_mul_f32 v[60:61], v[60:61], s[82:83] op_sel_hi:[1,0]
	v_pk_mul_f32 v[62:63], v[62:63], s[82:83] op_sel_hi:[1,0]
	v_pk_mul_f32 v[64:65], v[64:65], s[82:83] op_sel_hi:[1,0]
	v_rndne_f32_e32 v58, v58
	v_rndne_f32_e32 v59, v59
	v_rndne_f32_e32 v60, v60
	v_rndne_f32_e32 v61, v61
	v_rndne_f32_e32 v62, v62
	v_rndne_f32_e32 v63, v63
	v_rndne_f32_e32 v64, v64
	v_rndne_f32_e32 v65, v65
	v_cvt_u32_f32_e32 v62, v62
	v_cvt_u32_f32_e32 v63, v63
	v_cvt_u32_f32_e32 v58, v58
	v_cvt_u32_f32_e32 v59, v59
	v_cvt_u32_f32_sdwa v64, v64 dst_sel:WORD_1 dst_unused:UNUSED_PAD src0_sel:DWORD
	v_cvt_u32_f32_sdwa v60, v60 dst_sel:WORD_1 dst_unused:UNUSED_PAD src0_sel:DWORD
	v_cvt_u32_f32_sdwa v65, v65 dst_sel:BYTE_3 dst_unused:UNUSED_PAD src0_sel:DWORD
	v_cvt_u32_f32_sdwa v61, v61 dst_sel:BYTE_3 dst_unused:UNUSED_PAD src0_sel:DWORD
	v_lshl_or_b32 v62, v63, 8, v62
	v_lshl_or_b32 v63, v59, 8, v58
	v_or3_b32 v62, v62, v64, v65
	v_or3_b32 v63, v63, v60, v61
	global_store_dwordx2 v[164:165], v[62:63], off
	v_pk_mul_f32 v[54:55], v[54:55], v[172:173] op_sel_hi:[1,0]
	v_pk_mul_f32 v[56:57], v[56:57], v[172:173] op_sel_hi:[1,0]
	v_pk_mul_f32 v[50:51], v[50:51], v[172:173] op_sel_hi:[1,0]
	v_pk_mul_f32 v[52:53], v[52:53], v[172:173] op_sel_hi:[1,0]
	v_pk_add_f32 v[54:55], v[54:55], v[156:157]
	v_pk_add_f32 v[56:57], v[56:57], v[158:159]
	v_pk_add_f32 v[50:51], v[50:51], v[160:161]
	v_pk_add_f32 v[52:53], v[52:53], v[162:163]
	v_pk_mul_f32 v[50:51], v[50:51], s[50:51] op_sel_hi:[1,0]
	v_pk_mul_f32 v[52:53], v[52:53], s[50:51] op_sel_hi:[1,0]
	v_pk_mul_f32 v[54:55], v[54:55], s[50:51] op_sel_hi:[1,0]
	v_pk_mul_f32 v[56:57], v[56:57], s[50:51] op_sel_hi:[1,0]
	v_exp_f32_e32 v50, v50
	v_exp_f32_e32 v51, v51
	v_exp_f32_e32 v52, v52
	v_exp_f32_e32 v53, v53
	v_exp_f32_e32 v54, v54
	v_exp_f32_e32 v55, v55
	v_exp_f32_e32 v56, v56
	v_exp_f32_e32 v57, v57
	v_pk_add_f32 v[50:51], v[50:51], s[64:65] op_sel_hi:[1,0]
	v_pk_add_f32 v[52:53], v[52:53], s[64:65] op_sel_hi:[1,0]
	v_pk_add_f32 v[54:55], v[54:55], s[64:65] op_sel_hi:[1,0]
	v_pk_add_f32 v[56:57], v[56:57], s[64:65] op_sel_hi:[1,0]
	v_rcp_f32_e32 v50, v50
	v_rcp_f32_e32 v51, v51
	v_rcp_f32_e32 v52, v52
	v_rcp_f32_e32 v53, v53
	v_rcp_f32_e32 v54, v54
	v_rcp_f32_e32 v55, v55
	v_rcp_f32_e32 v56, v56
	v_rcp_f32_e32 v57, v57
	v_pk_mul_f32 v[50:51], v[50:51], s[82:83] op_sel_hi:[1,0]
	v_pk_mul_f32 v[52:53], v[52:53], s[82:83] op_sel_hi:[1,0]
	v_pk_mul_f32 v[54:55], v[54:55], s[82:83] op_sel_hi:[1,0]
	v_pk_mul_f32 v[56:57], v[56:57], s[82:83] op_sel_hi:[1,0]
	v_rndne_f32_e32 v50, v50
	v_rndne_f32_e32 v51, v51
	v_rndne_f32_e32 v52, v52
	v_rndne_f32_e32 v53, v53
	v_rndne_f32_e32 v54, v54
	v_rndne_f32_e32 v55, v55
	v_rndne_f32_e32 v56, v56
	v_rndne_f32_e32 v57, v57
	v_cvt_u32_f32_e32 v54, v54
	v_cvt_u32_f32_e32 v55, v55
	v_cvt_u32_f32_e32 v50, v50
	v_cvt_u32_f32_e32 v51, v51
	v_cvt_u32_f32_sdwa v56, v56 dst_sel:WORD_1 dst_unused:UNUSED_PAD src0_sel:DWORD
	v_cvt_u32_f32_sdwa v52, v52 dst_sel:WORD_1 dst_unused:UNUSED_PAD src0_sel:DWORD
	v_cvt_u32_f32_sdwa v57, v57 dst_sel:BYTE_3 dst_unused:UNUSED_PAD src0_sel:DWORD
	v_cvt_u32_f32_sdwa v53, v53 dst_sel:BYTE_3 dst_unused:UNUSED_PAD src0_sel:DWORD
	v_lshl_or_b32 v54, v55, 8, v54
	v_lshl_or_b32 v55, v51, 8, v50
	v_or3_b32 v54, v54, v56, v57
	v_or3_b32 v55, v55, v52, v53
	global_store_dwordx2 v[164:165], v[54:55], off offset:128
	v_lshl_add_u64 v[164:165], v[164:165], 0, s[8:9]
	v_ffbh_u32_e32 v174, v225
	v_min_u32_e32 v174, 32, v174
	v_lshlrev_b64 v[224:225], v174, v[224:225]
	v_min_u32_e32 v224, 1, v224
	v_or_b32_e32 v224, v225, v224
	v_cvt_f32_u32_e32 v224, v224
	v_sub_u32_e32 v225, 32, v174
	v_ldexp_f32 v224, v224, v225
	v_fmaak_f32 v224, v192, v224, 0x358637bd
	v_rsq_f32_e32 v172, v224
	s_nop 0
	v_pk_mul_f32 v[46:47], v[46:47], v[172:173] op_sel_hi:[1,0]
	v_pk_mul_f32 v[48:49], v[48:49], v[172:173] op_sel_hi:[1,0]
	v_pk_mul_f32 v[42:43], v[42:43], v[172:173] op_sel_hi:[1,0]
	v_pk_mul_f32 v[44:45], v[44:45], v[172:173] op_sel_hi:[1,0]
	v_pk_add_f32 v[46:47], v[46:47], v[148:149]
	v_pk_add_f32 v[48:49], v[48:49], v[150:151]
	v_pk_add_f32 v[42:43], v[42:43], v[152:153]
	v_pk_add_f32 v[44:45], v[44:45], v[154:155]
	v_pk_mul_f32 v[42:43], v[42:43], s[50:51] op_sel_hi:[1,0]
	v_pk_mul_f32 v[44:45], v[44:45], s[50:51] op_sel_hi:[1,0]
	v_pk_mul_f32 v[46:47], v[46:47], s[50:51] op_sel_hi:[1,0]
	v_pk_mul_f32 v[48:49], v[48:49], s[50:51] op_sel_hi:[1,0]
	v_exp_f32_e32 v42, v42
	v_exp_f32_e32 v43, v43
	v_exp_f32_e32 v44, v44
	v_exp_f32_e32 v45, v45
	v_exp_f32_e32 v46, v46
	v_exp_f32_e32 v47, v47
	v_exp_f32_e32 v48, v48
	v_exp_f32_e32 v49, v49
	v_pk_add_f32 v[42:43], v[42:43], s[64:65] op_sel_hi:[1,0]
	v_pk_add_f32 v[44:45], v[44:45], s[64:65] op_sel_hi:[1,0]
	v_pk_add_f32 v[46:47], v[46:47], s[64:65] op_sel_hi:[1,0]
	v_pk_add_f32 v[48:49], v[48:49], s[64:65] op_sel_hi:[1,0]
	v_rcp_f32_e32 v42, v42
	v_rcp_f32_e32 v43, v43
	v_rcp_f32_e32 v44, v44
	v_rcp_f32_e32 v45, v45
	v_rcp_f32_e32 v46, v46
	v_rcp_f32_e32 v47, v47
	v_rcp_f32_e32 v48, v48
	v_rcp_f32_e32 v49, v49
	v_pk_mul_f32 v[42:43], v[42:43], s[82:83] op_sel_hi:[1,0]
	v_pk_mul_f32 v[44:45], v[44:45], s[82:83] op_sel_hi:[1,0]
	v_pk_mul_f32 v[46:47], v[46:47], s[82:83] op_sel_hi:[1,0]
	v_pk_mul_f32 v[48:49], v[48:49], s[82:83] op_sel_hi:[1,0]
	v_rndne_f32_e32 v42, v42
	v_rndne_f32_e32 v43, v43
	v_rndne_f32_e32 v44, v44
	v_rndne_f32_e32 v45, v45
	v_rndne_f32_e32 v46, v46
	v_rndne_f32_e32 v47, v47
	v_rndne_f32_e32 v48, v48
	v_rndne_f32_e32 v49, v49
	v_cvt_u32_f32_e32 v46, v46
	v_cvt_u32_f32_e32 v47, v47
	v_cvt_u32_f32_e32 v42, v42
	v_cvt_u32_f32_e32 v43, v43
	v_cvt_u32_f32_sdwa v48, v48 dst_sel:WORD_1 dst_unused:UNUSED_PAD src0_sel:DWORD
	v_cvt_u32_f32_sdwa v44, v44 dst_sel:WORD_1 dst_unused:UNUSED_PAD src0_sel:DWORD
	v_cvt_u32_f32_sdwa v49, v49 dst_sel:BYTE_3 dst_unused:UNUSED_PAD src0_sel:DWORD
	v_cvt_u32_f32_sdwa v45, v45 dst_sel:BYTE_3 dst_unused:UNUSED_PAD src0_sel:DWORD
	v_lshl_or_b32 v46, v47, 8, v46
	v_lshl_or_b32 v47, v43, 8, v42
	v_or3_b32 v46, v46, v48, v49
	v_or3_b32 v47, v47, v44, v45
	global_store_dwordx2 v[164:165], v[46:47], off
	v_pk_mul_f32 v[38:39], v[38:39], v[172:173] op_sel_hi:[1,0]
	v_pk_mul_f32 v[40:41], v[40:41], v[172:173] op_sel_hi:[1,0]
	v_pk_mul_f32 v[34:35], v[34:35], v[172:173] op_sel_hi:[1,0]
	v_pk_mul_f32 v[36:37], v[36:37], v[172:173] op_sel_hi:[1,0]
	v_pk_add_f32 v[38:39], v[38:39], v[156:157]
	v_pk_add_f32 v[40:41], v[40:41], v[158:159]
	v_pk_add_f32 v[34:35], v[34:35], v[160:161]
	v_pk_add_f32 v[36:37], v[36:37], v[162:163]
	v_pk_mul_f32 v[34:35], v[34:35], s[50:51] op_sel_hi:[1,0]
	v_pk_mul_f32 v[36:37], v[36:37], s[50:51] op_sel_hi:[1,0]
	v_pk_mul_f32 v[38:39], v[38:39], s[50:51] op_sel_hi:[1,0]
	v_pk_mul_f32 v[40:41], v[40:41], s[50:51] op_sel_hi:[1,0]
	v_exp_f32_e32 v34, v34
	v_exp_f32_e32 v35, v35
	v_exp_f32_e32 v36, v36
	v_exp_f32_e32 v37, v37
	v_exp_f32_e32 v38, v38
	v_exp_f32_e32 v39, v39
	v_exp_f32_e32 v40, v40
	v_exp_f32_e32 v41, v41
	v_pk_add_f32 v[34:35], v[34:35], s[64:65] op_sel_hi:[1,0]
	v_pk_add_f32 v[36:37], v[36:37], s[64:65] op_sel_hi:[1,0]
	v_pk_add_f32 v[38:39], v[38:39], s[64:65] op_sel_hi:[1,0]
	v_pk_add_f32 v[40:41], v[40:41], s[64:65] op_sel_hi:[1,0]
	v_rcp_f32_e32 v34, v34
	v_rcp_f32_e32 v35, v35
	v_rcp_f32_e32 v36, v36
	v_rcp_f32_e32 v37, v37
	v_rcp_f32_e32 v38, v38
	v_rcp_f32_e32 v39, v39
	v_rcp_f32_e32 v40, v40
	v_rcp_f32_e32 v41, v41
	v_pk_mul_f32 v[34:35], v[34:35], s[82:83] op_sel_hi:[1,0]
	v_pk_mul_f32 v[36:37], v[36:37], s[82:83] op_sel_hi:[1,0]
	v_pk_mul_f32 v[38:39], v[38:39], s[82:83] op_sel_hi:[1,0]
	v_pk_mul_f32 v[40:41], v[40:41], s[82:83] op_sel_hi:[1,0]
	v_rndne_f32_e32 v34, v34
	v_rndne_f32_e32 v35, v35
	v_rndne_f32_e32 v36, v36
	v_rndne_f32_e32 v37, v37
	v_rndne_f32_e32 v38, v38
	v_rndne_f32_e32 v39, v39
	v_rndne_f32_e32 v40, v40
	v_rndne_f32_e32 v41, v41
	v_cvt_u32_f32_e32 v38, v38
	v_cvt_u32_f32_e32 v39, v39
	v_cvt_u32_f32_e32 v34, v34
	v_cvt_u32_f32_e32 v35, v35
	v_cvt_u32_f32_sdwa v40, v40 dst_sel:WORD_1 dst_unused:UNUSED_PAD src0_sel:DWORD
	v_cvt_u32_f32_sdwa v36, v36 dst_sel:WORD_1 dst_unused:UNUSED_PAD src0_sel:DWORD
	v_cvt_u32_f32_sdwa v41, v41 dst_sel:BYTE_3 dst_unused:UNUSED_PAD src0_sel:DWORD
	v_cvt_u32_f32_sdwa v37, v37 dst_sel:BYTE_3 dst_unused:UNUSED_PAD src0_sel:DWORD
	v_lshl_or_b32 v38, v39, 8, v38
	v_lshl_or_b32 v39, v35, 8, v34
	v_or3_b32 v38, v38, v40, v41
	v_or3_b32 v39, v39, v36, v37
	global_store_dwordx2 v[164:165], v[38:39], off offset:128
	v_lshl_add_u64 v[164:165], v[164:165], 0, s[8:9]
	v_ffbh_u32_e32 v174, v227
	v_min_u32_e32 v174, 32, v174
	v_lshlrev_b64 v[226:227], v174, v[226:227]
	v_min_u32_e32 v226, 1, v226
	v_or_b32_e32 v226, v227, v226
	v_cvt_f32_u32_e32 v226, v226
	v_sub_u32_e32 v227, 32, v174
	v_ldexp_f32 v226, v226, v227
	v_fmaak_f32 v226, v192, v226, 0x358637bd
	v_rsq_f32_e32 v172, v226
	s_nop 0
	v_pk_mul_f32 v[30:31], v[30:31], v[172:173] op_sel_hi:[1,0]
	v_pk_mul_f32 v[32:33], v[32:33], v[172:173] op_sel_hi:[1,0]
	v_pk_mul_f32 v[26:27], v[26:27], v[172:173] op_sel_hi:[1,0]
	v_pk_mul_f32 v[28:29], v[28:29], v[172:173] op_sel_hi:[1,0]
	v_pk_add_f32 v[30:31], v[30:31], v[148:149]
	v_pk_add_f32 v[32:33], v[32:33], v[150:151]
	v_pk_add_f32 v[26:27], v[26:27], v[152:153]
	v_pk_add_f32 v[28:29], v[28:29], v[154:155]
	v_pk_mul_f32 v[26:27], v[26:27], s[50:51] op_sel_hi:[1,0]
	v_pk_mul_f32 v[28:29], v[28:29], s[50:51] op_sel_hi:[1,0]
	v_pk_mul_f32 v[30:31], v[30:31], s[50:51] op_sel_hi:[1,0]
	v_pk_mul_f32 v[32:33], v[32:33], s[50:51] op_sel_hi:[1,0]
	v_exp_f32_e32 v26, v26
	v_exp_f32_e32 v27, v27
	v_exp_f32_e32 v28, v28
	v_exp_f32_e32 v29, v29
	v_exp_f32_e32 v30, v30
	v_exp_f32_e32 v31, v31
	v_exp_f32_e32 v32, v32
	v_exp_f32_e32 v33, v33
	v_pk_add_f32 v[26:27], v[26:27], s[64:65] op_sel_hi:[1,0]
	v_pk_add_f32 v[28:29], v[28:29], s[64:65] op_sel_hi:[1,0]
	v_pk_add_f32 v[30:31], v[30:31], s[64:65] op_sel_hi:[1,0]
	v_pk_add_f32 v[32:33], v[32:33], s[64:65] op_sel_hi:[1,0]
	v_rcp_f32_e32 v26, v26
	v_rcp_f32_e32 v27, v27
	v_rcp_f32_e32 v28, v28
	v_rcp_f32_e32 v29, v29
	v_rcp_f32_e32 v30, v30
	v_rcp_f32_e32 v31, v31
	v_rcp_f32_e32 v32, v32
	v_rcp_f32_e32 v33, v33
	v_pk_mul_f32 v[26:27], v[26:27], s[82:83] op_sel_hi:[1,0]
	v_pk_mul_f32 v[28:29], v[28:29], s[82:83] op_sel_hi:[1,0]
	v_pk_mul_f32 v[30:31], v[30:31], s[82:83] op_sel_hi:[1,0]
	v_pk_mul_f32 v[32:33], v[32:33], s[82:83] op_sel_hi:[1,0]
	v_rndne_f32_e32 v26, v26
	v_rndne_f32_e32 v27, v27
	v_rndne_f32_e32 v28, v28
	v_rndne_f32_e32 v29, v29
	v_rndne_f32_e32 v30, v30
	v_rndne_f32_e32 v31, v31
	v_rndne_f32_e32 v32, v32
	v_rndne_f32_e32 v33, v33
	v_cvt_u32_f32_e32 v30, v30
	v_cvt_u32_f32_e32 v31, v31
	v_cvt_u32_f32_e32 v26, v26
	v_cvt_u32_f32_e32 v27, v27
	v_cvt_u32_f32_sdwa v32, v32 dst_sel:WORD_1 dst_unused:UNUSED_PAD src0_sel:DWORD
	v_cvt_u32_f32_sdwa v28, v28 dst_sel:WORD_1 dst_unused:UNUSED_PAD src0_sel:DWORD
	v_cvt_u32_f32_sdwa v33, v33 dst_sel:BYTE_3 dst_unused:UNUSED_PAD src0_sel:DWORD
	v_cvt_u32_f32_sdwa v29, v29 dst_sel:BYTE_3 dst_unused:UNUSED_PAD src0_sel:DWORD
	v_lshl_or_b32 v30, v31, 8, v30
	v_lshl_or_b32 v31, v27, 8, v26
	v_or3_b32 v30, v30, v32, v33
	v_or3_b32 v31, v31, v28, v29
	global_store_dwordx2 v[164:165], v[30:31], off
	v_pk_mul_f32 v[22:23], v[22:23], v[172:173] op_sel_hi:[1,0]
	v_pk_mul_f32 v[24:25], v[24:25], v[172:173] op_sel_hi:[1,0]
	v_pk_mul_f32 v[18:19], v[18:19], v[172:173] op_sel_hi:[1,0]
	v_pk_mul_f32 v[20:21], v[20:21], v[172:173] op_sel_hi:[1,0]
	v_pk_add_f32 v[22:23], v[22:23], v[156:157]
	v_pk_add_f32 v[24:25], v[24:25], v[158:159]
	v_pk_add_f32 v[18:19], v[18:19], v[160:161]
	v_pk_add_f32 v[20:21], v[20:21], v[162:163]
	v_pk_mul_f32 v[18:19], v[18:19], s[50:51] op_sel_hi:[1,0]
	v_pk_mul_f32 v[20:21], v[20:21], s[50:51] op_sel_hi:[1,0]
	v_pk_mul_f32 v[22:23], v[22:23], s[50:51] op_sel_hi:[1,0]
	v_pk_mul_f32 v[24:25], v[24:25], s[50:51] op_sel_hi:[1,0]
	v_exp_f32_e32 v18, v18
	v_exp_f32_e32 v19, v19
	v_exp_f32_e32 v20, v20
	v_exp_f32_e32 v21, v21
	v_exp_f32_e32 v22, v22
	v_exp_f32_e32 v23, v23
	v_exp_f32_e32 v24, v24
	v_exp_f32_e32 v25, v25
	v_pk_add_f32 v[18:19], v[18:19], s[64:65] op_sel_hi:[1,0]
	v_pk_add_f32 v[20:21], v[20:21], s[64:65] op_sel_hi:[1,0]
	v_pk_add_f32 v[22:23], v[22:23], s[64:65] op_sel_hi:[1,0]
	v_pk_add_f32 v[24:25], v[24:25], s[64:65] op_sel_hi:[1,0]
	v_rcp_f32_e32 v18, v18
	v_rcp_f32_e32 v19, v19
	v_rcp_f32_e32 v20, v20
	v_rcp_f32_e32 v21, v21
	v_rcp_f32_e32 v22, v22
	v_rcp_f32_e32 v23, v23
	v_rcp_f32_e32 v24, v24
	v_rcp_f32_e32 v25, v25
	v_pk_mul_f32 v[18:19], v[18:19], s[82:83] op_sel_hi:[1,0]
	v_pk_mul_f32 v[20:21], v[20:21], s[82:83] op_sel_hi:[1,0]
	v_pk_mul_f32 v[22:23], v[22:23], s[82:83] op_sel_hi:[1,0]
	v_pk_mul_f32 v[24:25], v[24:25], s[82:83] op_sel_hi:[1,0]
	v_rndne_f32_e32 v18, v18
	v_rndne_f32_e32 v19, v19
	v_rndne_f32_e32 v20, v20
	v_rndne_f32_e32 v21, v21
	v_rndne_f32_e32 v22, v22
	v_rndne_f32_e32 v23, v23
	v_rndne_f32_e32 v24, v24
	v_rndne_f32_e32 v25, v25
	v_cvt_u32_f32_e32 v22, v22
	v_cvt_u32_f32_e32 v23, v23
	v_cvt_u32_f32_e32 v18, v18
	v_cvt_u32_f32_e32 v19, v19
	v_cvt_u32_f32_sdwa v24, v24 dst_sel:WORD_1 dst_unused:UNUSED_PAD src0_sel:DWORD
	v_cvt_u32_f32_sdwa v20, v20 dst_sel:WORD_1 dst_unused:UNUSED_PAD src0_sel:DWORD
	v_cvt_u32_f32_sdwa v25, v25 dst_sel:BYTE_3 dst_unused:UNUSED_PAD src0_sel:DWORD
	v_cvt_u32_f32_sdwa v21, v21 dst_sel:BYTE_3 dst_unused:UNUSED_PAD src0_sel:DWORD
	v_lshl_or_b32 v22, v23, 8, v22
	v_lshl_or_b32 v23, v19, 8, v18
	v_or3_b32 v22, v22, v24, v25
	v_or3_b32 v23, v23, v20, v21
	global_store_dwordx2 v[164:165], v[22:23], off offset:128
	v_lshl_add_u64 v[164:165], v[164:165], 0, s[8:9]
	v_ffbh_u32_e32 v174, v229
	v_min_u32_e32 v174, 32, v174
	v_lshlrev_b64 v[228:229], v174, v[228:229]
	v_min_u32_e32 v228, 1, v228
	v_or_b32_e32 v228, v229, v228
	v_cvt_f32_u32_e32 v228, v228
	v_sub_u32_e32 v229, 32, v174
	v_ldexp_f32 v228, v228, v229
	v_fmaak_f32 v228, v192, v228, 0x358637bd
	v_rsq_f32_e32 v172, v228
	s_nop 0
	v_pk_mul_f32 v[14:15], v[14:15], v[172:173] op_sel_hi:[1,0]
	v_pk_mul_f32 v[16:17], v[16:17], v[172:173] op_sel_hi:[1,0]
	v_pk_mul_f32 v[10:11], v[10:11], v[172:173] op_sel_hi:[1,0]
	v_pk_mul_f32 v[12:13], v[12:13], v[172:173] op_sel_hi:[1,0]
	v_pk_add_f32 v[14:15], v[14:15], v[148:149]
	v_pk_add_f32 v[16:17], v[16:17], v[150:151]
	v_pk_add_f32 v[10:11], v[10:11], v[152:153]
	v_pk_add_f32 v[12:13], v[12:13], v[154:155]
	v_pk_mul_f32 v[10:11], v[10:11], s[50:51] op_sel_hi:[1,0]
	v_pk_mul_f32 v[12:13], v[12:13], s[50:51] op_sel_hi:[1,0]
	v_pk_mul_f32 v[14:15], v[14:15], s[50:51] op_sel_hi:[1,0]
	v_pk_mul_f32 v[16:17], v[16:17], s[50:51] op_sel_hi:[1,0]
	v_exp_f32_e32 v10, v10
	v_exp_f32_e32 v11, v11
	v_exp_f32_e32 v12, v12
	v_exp_f32_e32 v13, v13
	v_exp_f32_e32 v14, v14
	v_exp_f32_e32 v15, v15
	v_exp_f32_e32 v16, v16
	v_exp_f32_e32 v17, v17
	v_pk_add_f32 v[10:11], v[10:11], s[64:65] op_sel_hi:[1,0]
	v_pk_add_f32 v[12:13], v[12:13], s[64:65] op_sel_hi:[1,0]
	v_pk_add_f32 v[14:15], v[14:15], s[64:65] op_sel_hi:[1,0]
	v_pk_add_f32 v[16:17], v[16:17], s[64:65] op_sel_hi:[1,0]
	v_rcp_f32_e32 v10, v10
	v_rcp_f32_e32 v11, v11
	v_rcp_f32_e32 v12, v12
	v_rcp_f32_e32 v13, v13
	v_rcp_f32_e32 v14, v14
	v_rcp_f32_e32 v15, v15
	v_rcp_f32_e32 v16, v16
	v_rcp_f32_e32 v17, v17
	v_pk_mul_f32 v[10:11], v[10:11], s[82:83] op_sel_hi:[1,0]
	v_pk_mul_f32 v[12:13], v[12:13], s[82:83] op_sel_hi:[1,0]
	v_pk_mul_f32 v[14:15], v[14:15], s[82:83] op_sel_hi:[1,0]
	v_pk_mul_f32 v[16:17], v[16:17], s[82:83] op_sel_hi:[1,0]
	v_rndne_f32_e32 v10, v10
	v_rndne_f32_e32 v11, v11
	v_rndne_f32_e32 v12, v12
	v_rndne_f32_e32 v13, v13
	v_rndne_f32_e32 v14, v14
	v_rndne_f32_e32 v15, v15
	v_rndne_f32_e32 v16, v16
	v_rndne_f32_e32 v17, v17
	v_cvt_u32_f32_e32 v14, v14
	v_cvt_u32_f32_e32 v15, v15
	v_cvt_u32_f32_e32 v10, v10
	v_cvt_u32_f32_e32 v11, v11
	v_cvt_u32_f32_sdwa v16, v16 dst_sel:WORD_1 dst_unused:UNUSED_PAD src0_sel:DWORD
	v_cvt_u32_f32_sdwa v12, v12 dst_sel:WORD_1 dst_unused:UNUSED_PAD src0_sel:DWORD
	v_cvt_u32_f32_sdwa v17, v17 dst_sel:BYTE_3 dst_unused:UNUSED_PAD src0_sel:DWORD
	v_cvt_u32_f32_sdwa v13, v13 dst_sel:BYTE_3 dst_unused:UNUSED_PAD src0_sel:DWORD
	v_lshl_or_b32 v14, v15, 8, v14
	v_lshl_or_b32 v15, v11, 8, v10
	v_or3_b32 v14, v14, v16, v17
	v_or3_b32 v15, v15, v12, v13
	global_store_dwordx2 v[164:165], v[14:15], off
	v_pk_mul_f32 v[6:7], v[6:7], v[172:173] op_sel_hi:[1,0]
	v_pk_mul_f32 v[8:9], v[8:9], v[172:173] op_sel_hi:[1,0]
	v_pk_mul_f32 v[2:3], v[2:3], v[172:173] op_sel_hi:[1,0]
	v_pk_mul_f32 v[4:5], v[4:5], v[172:173] op_sel_hi:[1,0]
	v_pk_add_f32 v[6:7], v[6:7], v[156:157]
	v_pk_add_f32 v[8:9], v[8:9], v[158:159]
	v_pk_add_f32 v[2:3], v[2:3], v[160:161]
	v_pk_add_f32 v[4:5], v[4:5], v[162:163]
	v_pk_mul_f32 v[2:3], v[2:3], s[50:51] op_sel_hi:[1,0]
	v_pk_mul_f32 v[4:5], v[4:5], s[50:51] op_sel_hi:[1,0]
	v_pk_mul_f32 v[6:7], v[6:7], s[50:51] op_sel_hi:[1,0]
	v_pk_mul_f32 v[8:9], v[8:9], s[50:51] op_sel_hi:[1,0]
	v_exp_f32_e32 v2, v2
	v_exp_f32_e32 v3, v3
	v_exp_f32_e32 v4, v4
	v_exp_f32_e32 v5, v5
	v_exp_f32_e32 v6, v6
	v_exp_f32_e32 v7, v7
	v_exp_f32_e32 v8, v8
	v_exp_f32_e32 v9, v9
	v_pk_add_f32 v[2:3], v[2:3], s[64:65] op_sel_hi:[1,0]
	v_pk_add_f32 v[4:5], v[4:5], s[64:65] op_sel_hi:[1,0]
	v_pk_add_f32 v[6:7], v[6:7], s[64:65] op_sel_hi:[1,0]
	v_pk_add_f32 v[8:9], v[8:9], s[64:65] op_sel_hi:[1,0]
	v_rcp_f32_e32 v2, v2
	v_rcp_f32_e32 v3, v3
	v_rcp_f32_e32 v4, v4
	v_rcp_f32_e32 v5, v5
	v_rcp_f32_e32 v6, v6
	v_rcp_f32_e32 v7, v7
	v_rcp_f32_e32 v8, v8
	v_rcp_f32_e32 v9, v9
	v_pk_mul_f32 v[2:3], v[2:3], s[82:83] op_sel_hi:[1,0]
	v_pk_mul_f32 v[4:5], v[4:5], s[82:83] op_sel_hi:[1,0]
	v_pk_mul_f32 v[6:7], v[6:7], s[82:83] op_sel_hi:[1,0]
	v_pk_mul_f32 v[8:9], v[8:9], s[82:83] op_sel_hi:[1,0]
	v_rndne_f32_e32 v2, v2
	v_rndne_f32_e32 v3, v3
	v_rndne_f32_e32 v4, v4
	v_rndne_f32_e32 v5, v5
	v_rndne_f32_e32 v6, v6
	v_rndne_f32_e32 v7, v7
	v_rndne_f32_e32 v8, v8
	v_rndne_f32_e32 v9, v9
	v_cvt_u32_f32_e32 v6, v6
	v_cvt_u32_f32_e32 v7, v7
	v_cvt_u32_f32_e32 v2, v2
	v_cvt_u32_f32_e32 v3, v3
	v_cvt_u32_f32_sdwa v8, v8 dst_sel:WORD_1 dst_unused:UNUSED_PAD src0_sel:DWORD
	v_cvt_u32_f32_sdwa v4, v4 dst_sel:WORD_1 dst_unused:UNUSED_PAD src0_sel:DWORD
	v_cvt_u32_f32_sdwa v9, v9 dst_sel:BYTE_3 dst_unused:UNUSED_PAD src0_sel:DWORD
	v_cvt_u32_f32_sdwa v5, v5 dst_sel:BYTE_3 dst_unused:UNUSED_PAD src0_sel:DWORD
	v_lshl_or_b32 v6, v7, 8, v6
	v_lshl_or_b32 v7, v3, 8, v2
	v_or3_b32 v6, v6, v8, v9
	v_or3_b32 v7, v7, v4, v5
	global_store_dwordx2 v[164:165], v[6:7], off offset:128
	s_branch .LBB0_1203
